# FFN-in SwiGLU epilogue with packed f32 ops in place on the accumulators (instruction selection lever)
# speedup vs baseline: 1.0106x; 1.0054x over previous
; __device__ __forceinline__ unsigned pk2(float lo, float hi) { f32x2_t v = {lo, hi}; bf16x2_t b = __builtin_convertvector(v, bf16x2_t); return __builtin_bit_cast(unsigned, b); }
; __device__ __forceinline__ float fast_sigmoid(float x) { return __builtin_amdgcn_rcpf(1.0f + __builtin_amdgcn_exp2f(-x * LOG2E)); }
; __device__ __forceinline__ void epi_all_run(const void* Pk_, int l, int s, const f32x4 (&acc)[2][2][4][2], const pg8::Unit& u, int wr, int wc, int fr, int fq) {
;     ...
;         if (s == 0 || s == 5) {
;             bf16_t* O = (bf16_t*)(ws + WS_ACT);
;             const int col0 = u.pn * 128 + wc * 32 + 8 * fq;
; #pragma unroll
;             for (int ai = 0; ai < 2; ++ai)
; #pragma unroll
;                 for (int m = 0; m < 4; ++m) {
;                     bf16_t* rowp = O + (size_t)(row0 + ai * 128 + m * 16) * DFF + col0;
;                     float r[8];
; #pragma unroll
;                     for (int n = 0; n < 2; ++n)
; #pragma unroll
;                         for (int j = 0; j < 4; ++j) { const float g = acc[ai][0][m][n][j], up = acc[ai][1][m][n][j]; r[n * 4 + j] = g * fast_sigmoid(g) * up; }
;                     v4u w; w.x = pk2(r[0], r[1]); w.y = pk2(r[2], r[3]); w.z = pk2(r[4], r[5]); w.w = pk2(r[6], r[7]);
;                     *(v4u*)rowp = w;
;                 }
.LBB0_125:
	s_and_b64 vcc, exec, s[38:39]
	s_cbranch_vccz .LBB0_124
	s_waitcnt lgkmcnt(0)
	v_lshl_or_b32 v130, s30, 7, v228
	s_mov_b32 s6, 0xbfb8aa3b
	v_ashrrev_i32_e32 v131, 31, v130
	s_mov_b64 s[4:5], 0x9500000
	v_lshl_add_u64 v[130:131], v[130:131], 1, s[34:35]
	s_movk_i32 s20, 0x1600
	v_lshl_add_u64 v[130:131], v[130:131], 0, s[4:5]
	v_pk_mul_f32 v[118:119], v[118:119], v[126:127]
	v_pk_mul_f32 v[120:121], v[120:121], v[128:129]
	v_pk_mul_f32 v[114:115], v[114:115], v[122:123]
	v_pk_mul_f32 v[116:117], v[116:117], v[124:125]
	v_pk_mul_f32 v[126:127], v[126:127], s[6:7] op_sel_hi:[1,0]
	v_pk_mul_f32 v[128:129], v[128:129], s[6:7] op_sel_hi:[1,0]
	v_pk_mul_f32 v[122:123], v[122:123], s[6:7] op_sel_hi:[1,0]
	v_pk_mul_f32 v[124:125], v[124:125], s[6:7] op_sel_hi:[1,0]
	v_exp_f32_e32 v126, v126
	v_exp_f32_e32 v127, v127
	v_exp_f32_e32 v128, v128
	v_exp_f32_e32 v129, v129
	v_exp_f32_e32 v122, v122
	v_exp_f32_e32 v123, v123
	v_exp_f32_e32 v124, v124
	v_exp_f32_e32 v125, v125
	v_pk_add_f32 v[126:127], v[126:127], 1.0 op_sel_hi:[1,0]
	v_pk_add_f32 v[128:129], v[128:129], 1.0 op_sel_hi:[1,0]
	v_pk_add_f32 v[122:123], v[122:123], 1.0 op_sel_hi:[1,0]
	v_pk_add_f32 v[124:125], v[124:125], 1.0 op_sel_hi:[1,0]
	v_rcp_f32_e32 v126, v126
	v_rcp_f32_e32 v127, v127
	v_rcp_f32_e32 v128, v128
	v_rcp_f32_e32 v129, v129
	v_rcp_f32_e32 v122, v122
	v_rcp_f32_e32 v123, v123
	v_rcp_f32_e32 v124, v124
	v_rcp_f32_e32 v125, v125
	v_pk_mul_f32 v[118:119], v[118:119], v[126:127]
	v_pk_mul_f32 v[120:121], v[120:121], v[128:129]
	v_pk_mul_f32 v[114:115], v[114:115], v[122:123]
	v_pk_mul_f32 v[116:117], v[116:117], v[124:125]
	v_cvt_pk_bf16_f32 v126, v118, v119
	v_cvt_pk_bf16_f32 v127, v120, v121
	v_cvt_pk_bf16_f32 v128, v114, v115
	v_cvt_pk_bf16_f32 v129, v116, v117
	v_mad_i64_i32 v[132:133], s[8:9], v184, s20, v[130:131]
	global_store_dwordx4 v[132:133], v[126:129], off
	v_pk_mul_f32 v[102:103], v[102:103], v[110:111]
	v_pk_mul_f32 v[104:105], v[104:105], v[112:113]
	v_pk_mul_f32 v[98:99], v[98:99], v[106:107]
	v_pk_mul_f32 v[100:101], v[100:101], v[108:109]
	v_pk_mul_f32 v[110:111], v[110:111], s[6:7] op_sel_hi:[1,0]
	v_pk_mul_f32 v[112:113], v[112:113], s[6:7] op_sel_hi:[1,0]
	v_pk_mul_f32 v[106:107], v[106:107], s[6:7] op_sel_hi:[1,0]
	v_pk_mul_f32 v[108:109], v[108:109], s[6:7] op_sel_hi:[1,0]
	v_exp_f32_e32 v110, v110
	v_exp_f32_e32 v111, v111
	v_exp_f32_e32 v112, v112
	v_exp_f32_e32 v113, v113
	v_exp_f32_e32 v106, v106
	v_exp_f32_e32 v107, v107
	v_exp_f32_e32 v108, v108
	v_exp_f32_e32 v109, v109
	v_pk_add_f32 v[110:111], v[110:111], 1.0 op_sel_hi:[1,0]
	v_pk_add_f32 v[112:113], v[112:113], 1.0 op_sel_hi:[1,0]
	v_pk_add_f32 v[106:107], v[106:107], 1.0 op_sel_hi:[1,0]
	v_pk_add_f32 v[108:109], v[108:109], 1.0 op_sel_hi:[1,0]
	v_rcp_f32_e32 v110, v110
	v_rcp_f32_e32 v111, v111
	v_rcp_f32_e32 v112, v112
	v_rcp_f32_e32 v113, v113
	v_rcp_f32_e32 v106, v106
	v_rcp_f32_e32 v107, v107
	v_rcp_f32_e32 v108, v108
	v_rcp_f32_e32 v109, v109
	v_pk_mul_f32 v[102:103], v[102:103], v[110:111]
	v_pk_mul_f32 v[104:105], v[104:105], v[112:113]
	v_pk_mul_f32 v[98:99], v[98:99], v[106:107]
	v_pk_mul_f32 v[100:101], v[100:101], v[108:109]
	v_cvt_pk_bf16_f32 v110, v102, v103
	v_cvt_pk_bf16_f32 v111, v104, v105
	v_cvt_pk_bf16_f32 v112, v98, v99
	v_cvt_pk_bf16_f32 v113, v100, v101
	v_mad_i64_i32 v[132:133], s[8:9], v186, s20, v[130:131]
	global_store_dwordx4 v[132:133], v[110:113], off
	v_pk_mul_f32 v[86:87], v[86:87], v[94:95]
	v_pk_mul_f32 v[88:89], v[88:89], v[96:97]
	v_pk_mul_f32 v[82:83], v[82:83], v[90:91]
	v_pk_mul_f32 v[84:85], v[84:85], v[92:93]
	v_pk_mul_f32 v[94:95], v[94:95], s[6:7] op_sel_hi:[1,0]
	v_pk_mul_f32 v[96:97], v[96:97], s[6:7] op_sel_hi:[1,0]
	v_pk_mul_f32 v[90:91], v[90:91], s[6:7] op_sel_hi:[1,0]
	v_pk_mul_f32 v[92:93], v[92:93], s[6:7] op_sel_hi:[1,0]
	v_exp_f32_e32 v94, v94
	v_exp_f32_e32 v95, v95
	v_exp_f32_e32 v96, v96
	v_exp_f32_e32 v97, v97
	v_exp_f32_e32 v90, v90
	v_exp_f32_e32 v91, v91
	v_exp_f32_e32 v92, v92
	v_exp_f32_e32 v93, v93
	v_pk_add_f32 v[94:95], v[94:95], 1.0 op_sel_hi:[1,0]
	v_pk_add_f32 v[96:97], v[96:97], 1.0 op_sel_hi:[1,0]
	v_pk_add_f32 v[90:91], v[90:91], 1.0 op_sel_hi:[1,0]
	v_pk_add_f32 v[92:93], v[92:93], 1.0 op_sel_hi:[1,0]
	v_rcp_f32_e32 v94, v94
	v_rcp_f32_e32 v95, v95
	v_rcp_f32_e32 v96, v96
	v_rcp_f32_e32 v97, v97
	v_rcp_f32_e32 v90, v90
	v_rcp_f32_e32 v91, v91
	v_rcp_f32_e32 v92, v92
	v_rcp_f32_e32 v93, v93
	v_pk_mul_f32 v[86:87], v[86:87], v[94:95]
	v_pk_mul_f32 v[88:89], v[88:89], v[96:97]
	v_pk_mul_f32 v[82:83], v[82:83], v[90:91]
	v_pk_mul_f32 v[84:85], v[84:85], v[92:93]
	v_cvt_pk_bf16_f32 v94, v86, v87
	v_cvt_pk_bf16_f32 v95, v88, v89
	v_cvt_pk_bf16_f32 v96, v82, v83
	v_cvt_pk_bf16_f32 v97, v84, v85
	v_or_b32_e32 v86, 32, v184
	v_mad_i64_i32 v[132:133], s[8:9], v86, s20, v[130:131]
	global_store_dwordx4 v[132:133], v[94:97], off
	v_pk_mul_f32 v[70:71], v[70:71], v[78:79]
	v_pk_mul_f32 v[72:73], v[72:73], v[80:81]
	v_pk_mul_f32 v[66:67], v[66:67], v[74:75]
	v_pk_mul_f32 v[68:69], v[68:69], v[76:77]
	v_pk_mul_f32 v[78:79], v[78:79], s[6:7] op_sel_hi:[1,0]
	v_pk_mul_f32 v[80:81], v[80:81], s[6:7] op_sel_hi:[1,0]
	v_pk_mul_f32 v[74:75], v[74:75], s[6:7] op_sel_hi:[1,0]
	v_pk_mul_f32 v[76:77], v[76:77], s[6:7] op_sel_hi:[1,0]
	v_exp_f32_e32 v78, v78
	v_exp_f32_e32 v79, v79
	v_exp_f32_e32 v80, v80
	v_exp_f32_e32 v81, v81
	v_exp_f32_e32 v74, v74
	v_exp_f32_e32 v75, v75
	v_exp_f32_e32 v76, v76
	v_exp_f32_e32 v77, v77
	v_pk_add_f32 v[78:79], v[78:79], 1.0 op_sel_hi:[1,0]
	v_pk_add_f32 v[80:81], v[80:81], 1.0 op_sel_hi:[1,0]
	v_pk_add_f32 v[74:75], v[74:75], 1.0 op_sel_hi:[1,0]
	v_pk_add_f32 v[76:77], v[76:77], 1.0 op_sel_hi:[1,0]
; __device__ __forceinline__ unsigned pk2(float lo, float hi) { f32x2_t v = {lo, hi}; bf16x2_t b = __builtin_convertvector(v, bf16x2_t); return __builtin_bit_cast(unsigned, b); }
; __device__ __forceinline__ float fast_sigmoid(float x) { return __builtin_amdgcn_rcpf(1.0f + __builtin_amdgcn_exp2f(-x * LOG2E)); }
; __device__ __forceinline__ void epi_all_run(const void* Pk_, int l, int s, const f32x4 (&acc)[2][2][4][2], const pg8::Unit& u, int wr, int wc, int fr, int fq) {
;     ...
; #pragma unroll
;             for (int ai = 0; ai < 2; ++ai)
; #pragma unroll
;                 for (int m = 0; m < 4; ++m) {
;                     bf16_t* rowp = O + (size_t)(row0 + ai * 128 + m * 16) * DFF + col0;
;                     float r[8];
; #pragma unroll
;                     for (int n = 0; n < 2; ++n)
; #pragma unroll
;                         for (int j = 0; j < 4; ++j) { const float g = acc[ai][0][m][n][j], up = acc[ai][1][m][n][j]; r[n * 4 + j] = g * fast_sigmoid(g) * up; }
;                     v4u w; w.x = pk2(r[0], r[1]); w.y = pk2(r[2], r[3]); w.z = pk2(r[4], r[5]); w.w = pk2(r[6], r[7]);
;                     *(v4u*)rowp = w;
;                 }
	v_rcp_f32_e32 v78, v78
	v_rcp_f32_e32 v79, v79
	v_rcp_f32_e32 v80, v80
	v_rcp_f32_e32 v81, v81
	v_rcp_f32_e32 v74, v74
	v_rcp_f32_e32 v75, v75
	v_rcp_f32_e32 v76, v76
	v_rcp_f32_e32 v77, v77
	v_pk_mul_f32 v[70:71], v[70:71], v[78:79]
	v_pk_mul_f32 v[72:73], v[72:73], v[80:81]
	v_pk_mul_f32 v[66:67], v[66:67], v[74:75]
	v_pk_mul_f32 v[68:69], v[68:69], v[76:77]
	v_cvt_pk_bf16_f32 v78, v70, v71
	v_cvt_pk_bf16_f32 v79, v72, v73
	v_cvt_pk_bf16_f32 v80, v66, v67
	v_cvt_pk_bf16_f32 v81, v68, v69
	v_or_b32_e32 v70, 48, v184
	v_mad_i64_i32 v[132:133], s[8:9], v70, s20, v[130:131]
	global_store_dwordx4 v[132:133], v[78:81], off
	v_pk_mul_f32 v[54:55], v[54:55], v[62:63]
	v_pk_mul_f32 v[56:57], v[56:57], v[64:65]
	v_pk_mul_f32 v[50:51], v[50:51], v[58:59]
	v_pk_mul_f32 v[52:53], v[52:53], v[60:61]
	v_pk_mul_f32 v[62:63], v[62:63], s[6:7] op_sel_hi:[1,0]
	v_pk_mul_f32 v[64:65], v[64:65], s[6:7] op_sel_hi:[1,0]
	v_pk_mul_f32 v[58:59], v[58:59], s[6:7] op_sel_hi:[1,0]
	v_pk_mul_f32 v[60:61], v[60:61], s[6:7] op_sel_hi:[1,0]
	v_exp_f32_e32 v62, v62
	v_exp_f32_e32 v63, v63
	v_exp_f32_e32 v64, v64
	v_exp_f32_e32 v65, v65
	v_exp_f32_e32 v58, v58
	v_exp_f32_e32 v59, v59
	v_exp_f32_e32 v60, v60
	v_exp_f32_e32 v61, v61
	v_pk_add_f32 v[62:63], v[62:63], 1.0 op_sel_hi:[1,0]
	v_pk_add_f32 v[64:65], v[64:65], 1.0 op_sel_hi:[1,0]
	v_pk_add_f32 v[58:59], v[58:59], 1.0 op_sel_hi:[1,0]
	v_pk_add_f32 v[60:61], v[60:61], 1.0 op_sel_hi:[1,0]
	v_rcp_f32_e32 v62, v62
	v_rcp_f32_e32 v63, v63
	v_rcp_f32_e32 v64, v64
	v_rcp_f32_e32 v65, v65
	v_rcp_f32_e32 v58, v58
	v_rcp_f32_e32 v59, v59
	v_rcp_f32_e32 v60, v60
	v_rcp_f32_e32 v61, v61
	v_pk_mul_f32 v[54:55], v[54:55], v[62:63]
	v_pk_mul_f32 v[56:57], v[56:57], v[64:65]
	v_pk_mul_f32 v[50:51], v[50:51], v[58:59]
	v_pk_mul_f32 v[52:53], v[52:53], v[60:61]
	v_cvt_pk_bf16_f32 v62, v54, v55
	v_cvt_pk_bf16_f32 v63, v56, v57
	v_cvt_pk_bf16_f32 v64, v50, v51
	v_cvt_pk_bf16_f32 v65, v52, v53
	v_add_u32_e32 v54, 0x80, v184
	v_mad_i64_i32 v[132:133], s[8:9], v54, s20, v[130:131]
	global_store_dwordx4 v[132:133], v[62:65], off
	v_pk_mul_f32 v[38:39], v[38:39], v[46:47]
	v_pk_mul_f32 v[40:41], v[40:41], v[48:49]
	v_pk_mul_f32 v[34:35], v[34:35], v[42:43]
	v_pk_mul_f32 v[36:37], v[36:37], v[44:45]
	v_pk_mul_f32 v[46:47], v[46:47], s[6:7] op_sel_hi:[1,0]
	v_pk_mul_f32 v[48:49], v[48:49], s[6:7] op_sel_hi:[1,0]
	v_pk_mul_f32 v[42:43], v[42:43], s[6:7] op_sel_hi:[1,0]
	v_pk_mul_f32 v[44:45], v[44:45], s[6:7] op_sel_hi:[1,0]
	v_exp_f32_e32 v46, v46
	v_exp_f32_e32 v47, v47
	v_exp_f32_e32 v48, v48
	v_exp_f32_e32 v49, v49
	v_exp_f32_e32 v42, v42
	v_exp_f32_e32 v43, v43
	v_exp_f32_e32 v44, v44
	v_exp_f32_e32 v45, v45
	v_pk_add_f32 v[46:47], v[46:47], 1.0 op_sel_hi:[1,0]
	v_pk_add_f32 v[48:49], v[48:49], 1.0 op_sel_hi:[1,0]
	v_pk_add_f32 v[42:43], v[42:43], 1.0 op_sel_hi:[1,0]
	v_pk_add_f32 v[44:45], v[44:45], 1.0 op_sel_hi:[1,0]
	v_rcp_f32_e32 v46, v46
	v_rcp_f32_e32 v47, v47
	v_rcp_f32_e32 v48, v48
	v_rcp_f32_e32 v49, v49
	v_rcp_f32_e32 v42, v42
	v_rcp_f32_e32 v43, v43
	v_rcp_f32_e32 v44, v44
	v_rcp_f32_e32 v45, v45
	v_pk_mul_f32 v[38:39], v[38:39], v[46:47]
	v_pk_mul_f32 v[40:41], v[40:41], v[48:49]
	v_pk_mul_f32 v[34:35], v[34:35], v[42:43]
	v_pk_mul_f32 v[36:37], v[36:37], v[44:45]
	v_cvt_pk_bf16_f32 v46, v38, v39
	v_cvt_pk_bf16_f32 v47, v40, v41
	v_cvt_pk_bf16_f32 v48, v34, v35
	v_cvt_pk_bf16_f32 v49, v36, v37
	v_add_u32_e32 v38, 0x90, v184
	v_mad_i64_i32 v[132:133], s[8:9], v38, s20, v[130:131]
	global_store_dwordx4 v[132:133], v[46:49], off
	v_pk_mul_f32 v[22:23], v[22:23], v[30:31]
	v_pk_mul_f32 v[24:25], v[24:25], v[32:33]
	v_pk_mul_f32 v[18:19], v[18:19], v[26:27]
	v_pk_mul_f32 v[20:21], v[20:21], v[28:29]
	v_pk_mul_f32 v[30:31], v[30:31], s[6:7] op_sel_hi:[1,0]
	v_pk_mul_f32 v[32:33], v[32:33], s[6:7] op_sel_hi:[1,0]
	v_pk_mul_f32 v[26:27], v[26:27], s[6:7] op_sel_hi:[1,0]
	v_pk_mul_f32 v[28:29], v[28:29], s[6:7] op_sel_hi:[1,0]
	v_exp_f32_e32 v30, v30
	v_exp_f32_e32 v31, v31
	v_exp_f32_e32 v32, v32
	v_exp_f32_e32 v33, v33
	v_exp_f32_e32 v26, v26
	v_exp_f32_e32 v27, v27
	v_exp_f32_e32 v28, v28
	v_exp_f32_e32 v29, v29
	v_pk_add_f32 v[30:31], v[30:31], 1.0 op_sel_hi:[1,0]
	v_pk_add_f32 v[32:33], v[32:33], 1.0 op_sel_hi:[1,0]
	v_pk_add_f32 v[26:27], v[26:27], 1.0 op_sel_hi:[1,0]
	v_pk_add_f32 v[28:29], v[28:29], 1.0 op_sel_hi:[1,0]
	v_rcp_f32_e32 v30, v30
	v_rcp_f32_e32 v31, v31
	v_rcp_f32_e32 v32, v32
	v_rcp_f32_e32 v33, v33
	v_rcp_f32_e32 v26, v26
	v_rcp_f32_e32 v27, v27
	v_rcp_f32_e32 v28, v28
	v_rcp_f32_e32 v29, v29
	v_pk_mul_f32 v[22:23], v[22:23], v[30:31]
	v_pk_mul_f32 v[24:25], v[24:25], v[32:33]
	v_pk_mul_f32 v[18:19], v[18:19], v[26:27]
	v_pk_mul_f32 v[20:21], v[20:21], v[28:29]
	v_cvt_pk_bf16_f32 v30, v22, v23
	v_cvt_pk_bf16_f32 v31, v24, v25
	v_cvt_pk_bf16_f32 v32, v18, v19
	v_cvt_pk_bf16_f32 v33, v20, v21
	v_add_u32_e32 v22, 0xa0, v184
	v_mad_i64_i32 v[132:133], s[8:9], v22, s20, v[130:131]
	global_store_dwordx4 v[132:133], v[30:33], off
	v_pk_mul_f32 v[6:7], v[6:7], v[14:15]
	v_pk_mul_f32 v[8:9], v[8:9], v[16:17]
	v_pk_mul_f32 v[2:3], v[2:3], v[10:11]
	v_pk_mul_f32 v[4:5], v[4:5], v[12:13]
	v_pk_mul_f32 v[14:15], v[14:15], s[6:7] op_sel_hi:[1,0]
	v_pk_mul_f32 v[16:17], v[16:17], s[6:7] op_sel_hi:[1,0]
	v_pk_mul_f32 v[10:11], v[10:11], s[6:7] op_sel_hi:[1,0]
	v_pk_mul_f32 v[12:13], v[12:13], s[6:7] op_sel_hi:[1,0]
	v_exp_f32_e32 v14, v14
	v_exp_f32_e32 v15, v15
	v_exp_f32_e32 v16, v16
	v_exp_f32_e32 v17, v17
	v_exp_f32_e32 v10, v10
	v_exp_f32_e32 v11, v11
	v_exp_f32_e32 v12, v12
	v_exp_f32_e32 v13, v13
	v_pk_add_f32 v[14:15], v[14:15], 1.0 op_sel_hi:[1,0]
	v_pk_add_f32 v[16:17], v[16:17], 1.0 op_sel_hi:[1,0]
	v_pk_add_f32 v[10:11], v[10:11], 1.0 op_sel_hi:[1,0]
	v_pk_add_f32 v[12:13], v[12:13], 1.0 op_sel_hi:[1,0]
	v_rcp_f32_e32 v14, v14
	v_rcp_f32_e32 v15, v15
	v_rcp_f32_e32 v16, v16
	v_rcp_f32_e32 v17, v17
	v_rcp_f32_e32 v10, v10
	v_rcp_f32_e32 v11, v11
	v_rcp_f32_e32 v12, v12
	v_rcp_f32_e32 v13, v13
	v_pk_mul_f32 v[6:7], v[6:7], v[14:15]
	v_pk_mul_f32 v[8:9], v[8:9], v[16:17]
	v_pk_mul_f32 v[2:3], v[2:3], v[10:11]
	v_pk_mul_f32 v[4:5], v[4:5], v[12:13]
	v_cvt_pk_bf16_f32 v14, v6, v7
	v_cvt_pk_bf16_f32 v15, v8, v9
	v_cvt_pk_bf16_f32 v16, v2, v3
	v_cvt_pk_bf16_f32 v17, v4, v5
	v_add_u32_e32 v6, 0xb0, v184
	v_mad_i64_i32 v[132:133], s[8:9], v6, s20, v[130:131]
	global_store_dwordx4 v[132:133], v[14:17], off
	s_and_b64 vcc, exec, s[44:45]
	s_mov_b64 s[4:5], -1
	s_cbranch_vccnz .LBB0_51
